# softmax+PV wave role runs at s_setprio 2 (QK role at 0) in the attention loop
# speedup vs baseline: 1.0638x; 1.0090x over previous
.Latt2_wd_2:
	s_setprio 2
	ds_read_b128 v[236:239], v216 offset:25600
	ds_read_b128 v[240:243], v216 offset:30208
	ds_read_b128 v[244:247], v216 offset:34816
	ds_read_b128 v[248:251], v216 offset:39424
	ds_read_b128 v[210:213], v216 offset:25632
	s_nop 4
	v_max_f32_e32 v186, v83, v83
	v_max_f32_e32 v187, v82, v82
	v_max_f32_e32 v186, v187, v186
	v_max3_f32 v186, v186, v84, v85
	v_max3_f32 v186, v186, v86, v87
	v_max3_f32 v186, v186, v88, v89
	v_max3_f32 v186, v186, v90, v91
	v_max3_f32 v186, v186, v92, v93
	v_max3_f32 v186, v186, v94, v95
	v_max3_f32 v186, v186, v96, v97
	v_max3_f32 v186, v186, v66, v67
	v_max3_f32 v186, v186, v68, v69
	v_max3_f32 v186, v186, v70, v71
	v_max3_f32 v186, v186, v72, v73
	v_max3_f32 v186, v186, v74, v75
	v_max3_f32 v186, v186, v76, v77
	v_max3_f32 v186, v186, v78, v79
	v_max3_f32 v186, v186, v80, v81
	ds_bpermute_b32 v187, v214, v186
	s_waitcnt lgkmcnt(0)
	v_max_f32_e32 v187, v187, v187
	v_max_f32_e32 v187, v186, v187
	v_add_f32_e32 v186, 0x41380000, v223
	v_cmp_gt_f32_e32 vcc, v187, v186
	s_cbranch_vccz .Latt2_nr_3
	v_max_f32_e32 v186, v187, v187
	v_max_f32_e32 v187, v223, v223
	v_max_f32_e32 v187, v187, v186
	v_sub_f32_e32 v186, v223, v187
	v_exp_f32_e32 v186, v186
	v_mov_b32_e32 v223, v187
	v_pk_mul_f32 v[64:65], v[64:65], v[186:187] op_sel_hi:[1,0]
	v_pk_mul_f32 v[62:63], v[62:63], v[186:187] op_sel_hi:[1,0]
	v_pk_mul_f32 v[60:61], v[60:61], v[186:187] op_sel_hi:[1,0]
	v_pk_mul_f32 v[58:59], v[58:59], v[186:187] op_sel_hi:[1,0]
	v_pk_mul_f32 v[56:57], v[56:57], v[186:187] op_sel_hi:[1,0]
	v_pk_mul_f32 v[54:55], v[54:55], v[186:187] op_sel_hi:[1,0]
	v_pk_mul_f32 v[52:53], v[52:53], v[186:187] op_sel_hi:[1,0]
	v_pk_mul_f32 v[50:51], v[50:51], v[186:187] op_sel_hi:[1,0]
	v_pk_mul_f32 v[48:49], v[48:49], v[186:187] op_sel_hi:[1,0]
	v_pk_mul_f32 v[46:47], v[46:47], v[186:187] op_sel_hi:[1,0]
	v_pk_mul_f32 v[44:45], v[44:45], v[186:187] op_sel_hi:[1,0]
	v_pk_mul_f32 v[42:43], v[42:43], v[186:187] op_sel_hi:[1,0]
	v_pk_mul_f32 v[40:41], v[40:41], v[186:187] op_sel_hi:[1,0]
	v_pk_mul_f32 v[38:39], v[38:39], v[186:187] op_sel_hi:[1,0]
	v_pk_mul_f32 v[36:37], v[36:37], v[186:187] op_sel_hi:[1,0]
	v_pk_mul_f32 v[34:35], v[34:35], v[186:187] op_sel_hi:[1,0]
	v_pk_mul_f32 v[32:33], v[32:33], v[186:187] op_sel_hi:[1,0]
	v_pk_mul_f32 v[30:31], v[30:31], v[186:187] op_sel_hi:[1,0]
	v_pk_mul_f32 v[28:29], v[28:29], v[186:187] op_sel_hi:[1,0]
	v_pk_mul_f32 v[26:27], v[26:27], v[186:187] op_sel_hi:[1,0]
	v_pk_mul_f32 v[24:25], v[24:25], v[186:187] op_sel_hi:[1,0]
	v_pk_mul_f32 v[22:23], v[22:23], v[186:187] op_sel_hi:[1,0]
	v_pk_mul_f32 v[20:21], v[20:21], v[186:187] op_sel_hi:[1,0]
	v_pk_mul_f32 v[18:19], v[18:19], v[186:187] op_sel_hi:[1,0]
	v_pk_mul_f32 v[16:17], v[16:17], v[186:187] op_sel_hi:[1,0]
	v_pk_mul_f32 v[14:15], v[14:15], v[186:187] op_sel_hi:[1,0]
	v_pk_mul_f32 v[12:13], v[12:13], v[186:187] op_sel_hi:[1,0]
	v_pk_mul_f32 v[10:11], v[10:11], v[186:187] op_sel_hi:[1,0]
	v_pk_mul_f32 v[8:9], v[8:9], v[186:187] op_sel_hi:[1,0]
	v_pk_mul_f32 v[6:7], v[6:7], v[186:187] op_sel_hi:[1,0]
	v_pk_mul_f32 v[4:5], v[4:5], v[186:187] op_sel_hi:[1,0]
	v_pk_mul_f32 v[2:3], v[2:3], v[186:187] op_sel_hi:[1,0]
	v_mul_f32_e32 v224, v224, v186
.Latt2_nr_3:
	v_sub_f32_e32 v82, v82, v223
	v_sub_f32_e32 v83, v83, v223
	v_sub_f32_e32 v84, v84, v223
	v_sub_f32_e32 v85, v85, v223
	v_exp_f32_e32 v82, v82
	v_exp_f32_e32 v83, v83
	v_exp_f32_e32 v84, v84
	v_exp_f32_e32 v85, v85
	v_sub_f32_e32 v86, v86, v223
	v_sub_f32_e32 v87, v87, v223
	v_sub_f32_e32 v88, v88, v223
	v_sub_f32_e32 v89, v89, v223
	v_exp_f32_e32 v86, v86
	v_exp_f32_e32 v87, v87
	v_exp_f32_e32 v88, v88
	v_exp_f32_e32 v89, v89
	v_cvt_pk_bf16_f32 v226, v82, v83
	v_cvt_pk_bf16_f32 v227, v84, v85
	v_cvt_pk_bf16_f32 v228, v86, v87
	v_cvt_pk_bf16_f32 v229, v88, v89
	s_nop 1
	v_mfma_f32_32x32x16_bf16 v[50:65], v[236:239], v[226:229], v[50:65]
	ds_read_b128 v[236:239], v216 offset:30240
	v_sub_f32_e32 v90, v90, v223
	v_sub_f32_e32 v91, v91, v223
	v_sub_f32_e32 v92, v92, v223
	v_sub_f32_e32 v93, v93, v223
	v_exp_f32_e32 v90, v90
	v_exp_f32_e32 v91, v91
	v_mfma_f32_32x32x16_bf16 v[34:49], v[240:243], v[226:229], v[34:49]
	ds_read_b128 v[240:243], v216 offset:34848
	v_exp_f32_e32 v92, v92
	v_exp_f32_e32 v93, v93
	v_sub_f32_e32 v94, v94, v223
	v_sub_f32_e32 v95, v95, v223
	v_sub_f32_e32 v96, v96, v223
	v_sub_f32_e32 v97, v97, v223
	v_mfma_f32_32x32x16_bf16 v[18:33], v[244:247], v[226:229], v[18:33]
	ds_read_b128 v[244:247], v216 offset:39456
	v_exp_f32_e32 v94, v94
	v_exp_f32_e32 v95, v95
	v_exp_f32_e32 v96, v96
	v_exp_f32_e32 v97, v97
	v_add_f32_e32 v186, 0, v82
	v_add_f32_e32 v186, v83, v186
	v_mfma_f32_32x32x16_bf16 v[2:17], v[248:251], v[226:229], v[2:17]
	ds_read_b128 v[248:251], v216 offset:25664
	v_add_f32_e32 v186, v84, v186
	v_add_f32_e32 v186, v85, v186
	v_add_f32_e32 v186, v86, v186
	v_add_f32_e32 v186, v87, v186
	v_add_f32_e32 v186, v88, v186
	v_add_f32_e32 v186, v89, v186
	v_cvt_pk_bf16_f32 v226, v90, v91
	v_cvt_pk_bf16_f32 v227, v92, v93
	v_cvt_pk_bf16_f32 v228, v94, v95
	v_cvt_pk_bf16_f32 v229, v96, v97
	s_nop 1
	v_mfma_f32_32x32x16_bf16 v[50:65], v[210:213], v[226:229], v[50:65]
	ds_read_b128 v[210:213], v216 offset:30272
	v_sub_f32_e32 v66, v66, v223
	v_sub_f32_e32 v67, v67, v223
	v_sub_f32_e32 v68, v68, v223
	v_sub_f32_e32 v69, v69, v223
	v_exp_f32_e32 v66, v66
	v_exp_f32_e32 v67, v67
	s_waitcnt lgkmcnt(4)
	v_mfma_f32_32x32x16_bf16 v[34:49], v[236:239], v[226:229], v[34:49]
	ds_read_b128 v[236:239], v216 offset:34880
	v_exp_f32_e32 v68, v68
	v_exp_f32_e32 v69, v69
	v_sub_f32_e32 v70, v70, v223
	v_sub_f32_e32 v71, v71, v223
	v_sub_f32_e32 v72, v72, v223
	v_sub_f32_e32 v73, v73, v223
	s_waitcnt lgkmcnt(4)
	v_mfma_f32_32x32x16_bf16 v[18:33], v[240:243], v[226:229], v[18:33]
	ds_read_b128 v[240:243], v216 offset:39488
	v_exp_f32_e32 v70, v70
	v_exp_f32_e32 v71, v71
	v_exp_f32_e32 v72, v72
	v_exp_f32_e32 v73, v73
	v_add_f32_e32 v186, v90, v186
	v_add_f32_e32 v186, v91, v186
	s_waitcnt lgkmcnt(4)
	v_mfma_f32_32x32x16_bf16 v[2:17], v[244:247], v[226:229], v[2:17]
	ds_read_b128 v[244:247], v216 offset:25696
	v_add_f32_e32 v186, v92, v186
	v_add_f32_e32 v186, v93, v186
	v_add_f32_e32 v186, v94, v186
	v_add_f32_e32 v186, v95, v186
	v_add_f32_e32 v186, v96, v186
	v_add_f32_e32 v186, v97, v186
	v_cvt_pk_bf16_f32 v226, v66, v67
	v_cvt_pk_bf16_f32 v227, v68, v69
	v_cvt_pk_bf16_f32 v228, v70, v71
	v_cvt_pk_bf16_f32 v229, v72, v73
	s_nop 1
	s_waitcnt lgkmcnt(4)
	v_mfma_f32_32x32x16_bf16 v[50:65], v[248:251], v[226:229], v[50:65]
	ds_read_b128 v[248:251], v216 offset:30304
	v_sub_f32_e32 v74, v74, v223
	v_sub_f32_e32 v75, v75, v223
	v_sub_f32_e32 v76, v76, v223
	v_sub_f32_e32 v77, v77, v223
	v_exp_f32_e32 v74, v74
	v_exp_f32_e32 v75, v75
	s_waitcnt lgkmcnt(4)
	v_mfma_f32_32x32x16_bf16 v[34:49], v[210:213], v[226:229], v[34:49]
	ds_read_b128 v[210:213], v216 offset:34912
	v_exp_f32_e32 v76, v76
	v_exp_f32_e32 v77, v77
	v_sub_f32_e32 v78, v78, v223
	v_sub_f32_e32 v79, v79, v223
	v_sub_f32_e32 v80, v80, v223
	v_sub_f32_e32 v81, v81, v223
	s_waitcnt lgkmcnt(4)
	v_mfma_f32_32x32x16_bf16 v[18:33], v[236:239], v[226:229], v[18:33]
	ds_read_b128 v[236:239], v216 offset:39520
	v_exp_f32_e32 v78, v78
	v_exp_f32_e32 v79, v79
	v_exp_f32_e32 v80, v80
	v_exp_f32_e32 v81, v81
	v_add_f32_e32 v186, v66, v186
	v_add_f32_e32 v186, v67, v186
	s_waitcnt lgkmcnt(4)
	v_mfma_f32_32x32x16_bf16 v[2:17], v[240:243], v[226:229], v[2:17]
	v_add_f32_e32 v186, v68, v186
	v_add_f32_e32 v186, v69, v186
	v_add_f32_e32 v186, v70, v186
	v_add_f32_e32 v186, v71, v186
	v_add_f32_e32 v186, v72, v186
	v_add_f32_e32 v186, v73, v186
	v_cvt_pk_bf16_f32 v226, v74, v75
	v_cvt_pk_bf16_f32 v227, v76, v77
	v_cvt_pk_bf16_f32 v228, v78, v79
	v_cvt_pk_bf16_f32 v229, v80, v81
	s_nop 1
	s_waitcnt lgkmcnt(3)
	v_mfma_f32_32x32x16_bf16 v[50:65], v[244:247], v[226:229], v[50:65]
	v_add_f32_e32 v186, v74, v186
	v_add_f32_e32 v186, v75, v186
	s_waitcnt lgkmcnt(2)
	v_mfma_f32_32x32x16_bf16 v[34:49], v[248:251], v[226:229], v[34:49]
	v_add_f32_e32 v186, v76, v186
	v_add_f32_e32 v186, v77, v186
	s_waitcnt lgkmcnt(1)
	v_mfma_f32_32x32x16_bf16 v[18:33], v[210:213], v[226:229], v[18:33]
	v_add_f32_e32 v186, v78, v186
	v_add_f32_e32 v186, v79, v186
	s_waitcnt lgkmcnt(0)
	s_barrier
	v_mfma_f32_32x32x16_bf16 v[2:17], v[236:239], v[226:229], v[2:17]
	v_add_f32_e32 v186, v80, v186
	v_add_f32_e32 v186, v81, v186
	v_add_f32_e32 v225, v224, v186
	s_setprio 0
	ds_read_b128 v[226:229], v215 offset:44032
	ds_read_b128 v[236:239], v215 offset:56832
	ds_read_b128 v[240:243], v215 offset:44064
	ds_read_b128 v[244:247], v215 offset:56864
	ds_read_b128 v[248:251], v215 offset:44096
	ds_read_b128 v[210:213], v215 offset:56896
	s_waitcnt lgkmcnt(5)
	v_mfma_f32_32x32x16_bf16 v[82:97], v[226:229], v[126:129], 0
	ds_read_b128 v[226:229], v215 offset:44128
	s_waitcnt lgkmcnt(5)
	v_mfma_f32_32x32x16_bf16 v[66:81], v[236:239], v[126:129], 0
	ds_read_b128 v[236:239], v215 offset:56928
	s_waitcnt lgkmcnt(5)
	v_mfma_f32_32x32x16_bf16 v[82:97], v[240:243], v[142:145], v[82:97]
	ds_read_b128 v[240:243], v215 offset:44160
	s_waitcnt lgkmcnt(5)
	v_mfma_f32_32x32x16_bf16 v[66:81], v[244:247], v[142:145], v[66:81]
	ds_read_b128 v[244:247], v215 offset:56960
	s_waitcnt lgkmcnt(5)
	v_mfma_f32_32x32x16_bf16 v[82:97], v[248:251], v[146:149], v[82:97]
	ds_read_b128 v[248:251], v215 offset:44192
	s_waitcnt lgkmcnt(5)
	v_mfma_f32_32x32x16_bf16 v[66:81], v[210:213], v[146:149], v[66:81]
	ds_read_b128 v[210:213], v215 offset:56992
	s_waitcnt lgkmcnt(5)
	v_mfma_f32_32x32x16_bf16 v[82:97], v[226:229], v[150:153], v[82:97]
	ds_read_b128 v[226:229], v215 offset:44224
	s_waitcnt lgkmcnt(5)
	v_mfma_f32_32x32x16_bf16 v[66:81], v[236:239], v[150:153], v[66:81]
	ds_read_b128 v[236:239], v215 offset:57024
	s_waitcnt lgkmcnt(5)
	v_mfma_f32_32x32x16_bf16 v[82:97], v[240:243], v[154:157], v[82:97]
	ds_read_b128 v[240:243], v215 offset:44256
	s_waitcnt lgkmcnt(5)
	v_mfma_f32_32x32x16_bf16 v[66:81], v[244:247], v[154:157], v[66:81]
	ds_read_b128 v[244:247], v215 offset:57056
	s_waitcnt lgkmcnt(5)
	v_mfma_f32_32x32x16_bf16 v[82:97], v[248:251], v[158:161], v[82:97]
	ds_read_b128 v[248:251], v215 offset:44288
	s_waitcnt lgkmcnt(5)
	v_mfma_f32_32x32x16_bf16 v[66:81], v[210:213], v[158:161], v[66:81]
	ds_read_b128 v[210:213], v215 offset:57088
	s_waitcnt lgkmcnt(5)
	v_mfma_f32_32x32x16_bf16 v[82:97], v[226:229], v[162:165], v[82:97]
	ds_read_b128 v[226:229], v215 offset:44320
	s_waitcnt lgkmcnt(5)
	v_mfma_f32_32x32x16_bf16 v[66:81], v[236:239], v[162:165], v[66:81]
	ds_read_b128 v[236:239], v215 offset:57120
	s_waitcnt lgkmcnt(5)
	v_mfma_f32_32x32x16_bf16 v[82:97], v[240:243], v[166:169], v[82:97]
	ds_read_b128 v[240:243], v215 offset:44352
	s_waitcnt lgkmcnt(5)
	v_mfma_f32_32x32x16_bf16 v[66:81], v[244:247], v[166:169], v[66:81]
	ds_read_b128 v[244:247], v215 offset:57152
	s_waitcnt lgkmcnt(5)
	v_mfma_f32_32x32x16_bf16 v[82:97], v[248:251], v[170:173], v[82:97]
	ds_read_b128 v[248:251], v215 offset:44384
	s_waitcnt lgkmcnt(5)
	v_mfma_f32_32x32x16_bf16 v[66:81], v[210:213], v[170:173], v[66:81]
	ds_read_b128 v[210:213], v215 offset:57184
	s_waitcnt lgkmcnt(5)
	v_mfma_f32_32x32x16_bf16 v[82:97], v[226:229], v[174:177], v[82:97]
	s_waitcnt lgkmcnt(4)
	v_mfma_f32_32x32x16_bf16 v[66:81], v[236:239], v[174:177], v[66:81]
	s_waitcnt lgkmcnt(3)
	v_mfma_f32_32x32x16_bf16 v[82:97], v[240:243], v[178:181], v[82:97]
	s_waitcnt lgkmcnt(2)
	v_mfma_f32_32x32x16_bf16 v[66:81], v[244:247], v[178:181], v[66:81]
	s_waitcnt lgkmcnt(1)
	v_mfma_f32_32x32x16_bf16 v[82:97], v[248:251], v[182:185], v[82:97]
	s_waitcnt lgkmcnt(0)
	s_barrier
	v_mfma_f32_32x32x16_bf16 v[66:81], v[210:213], v[182:185], v[66:81]
	s_add_i32 s13, s11, -2
	s_cmp_ge_u32 s13, s5
	s_cbranch_scc1 .Latt2_ws_4
	s_waitcnt vmcnt(9)
	ds_write_b128 v219, v[118:121]
	s_waitcnt vmcnt(8)
	ds_write_b128 v220, v[122:125]
	s_waitcnt vmcnt(7)
	ds_write_b128 v221, v[130:133]
	s_waitcnt vmcnt(6)
	ds_write_b128 v222, v[134:137] offset:25600
	s_waitcnt vmcnt(5)
	ds_write_b128 v222, v[138:141] offset:34816

.Latt2_wl_5:
	s_mov_b64 s[14:15], 0xc000
	v_lshl_add_u64 v[206:207], v[206:207], 0, s[14:15]
	s_mov_b64 s[14:15], 0x100
	s_add_i32 s11, s11, 2
	v_lshl_add_u64 v[204:205], v[204:205], 0, s[14:15]
	v_lshl_add_u64 v[208:209], v[208:209], 0, s[14:15]
	s_setprio 2
	ds_read_b128 v[236:239], v217
	ds_read_b128 v[240:243], v217 offset:4608
	ds_read_b128 v[244:247], v217 offset:9216
	ds_read_b128 v[248:251], v217 offset:13824
	ds_read_b128 v[210:213], v217 offset:32
	s_nop 4
	v_max_f32_e32 v186, v83, v83
	v_max_f32_e32 v187, v82, v82
	v_max_f32_e32 v186, v187, v186
	v_max3_f32 v186, v186, v84, v85
	v_max3_f32 v186, v186, v86, v87
	v_max3_f32 v186, v186, v88, v89
	v_max3_f32 v186, v186, v90, v91
	v_max3_f32 v186, v186, v92, v93
	v_max3_f32 v186, v186, v94, v95
	v_max3_f32 v186, v186, v96, v97
	v_max3_f32 v186, v186, v66, v67
	v_max3_f32 v186, v186, v68, v69
	v_max3_f32 v186, v186, v70, v71
	v_max3_f32 v186, v186, v72, v73
	v_max3_f32 v186, v186, v74, v75
	v_max3_f32 v186, v186, v76, v77
	v_max3_f32 v186, v186, v78, v79
	v_max3_f32 v186, v186, v80, v81
	ds_bpermute_b32 v187, v214, v186
	s_waitcnt lgkmcnt(0)
	v_max_f32_e32 v187, v187, v187
	v_max_f32_e32 v187, v186, v187
	v_add_f32_e32 v186, 0x41380000, v223
	v_cmp_gt_f32_e32 vcc, v187, v186
	s_cbranch_vccz .Latt2_nr_6
	v_max_f32_e32 v186, v187, v187
	v_max_f32_e32 v187, v223, v223
	v_max_f32_e32 v187, v187, v186
	v_sub_f32_e32 v186, v223, v187
	v_exp_f32_e32 v186, v186
	v_mov_b32_e32 v223, v187
	v_pk_mul_f32 v[64:65], v[64:65], v[186:187] op_sel_hi:[1,0]
	v_pk_mul_f32 v[62:63], v[62:63], v[186:187] op_sel_hi:[1,0]
	v_pk_mul_f32 v[60:61], v[60:61], v[186:187] op_sel_hi:[1,0]
	v_pk_mul_f32 v[58:59], v[58:59], v[186:187] op_sel_hi:[1,0]
	v_pk_mul_f32 v[56:57], v[56:57], v[186:187] op_sel_hi:[1,0]
	v_pk_mul_f32 v[54:55], v[54:55], v[186:187] op_sel_hi:[1,0]
	v_pk_mul_f32 v[52:53], v[52:53], v[186:187] op_sel_hi:[1,0]
	v_pk_mul_f32 v[50:51], v[50:51], v[186:187] op_sel_hi:[1,0]
	v_pk_mul_f32 v[48:49], v[48:49], v[186:187] op_sel_hi:[1,0]
	v_pk_mul_f32 v[46:47], v[46:47], v[186:187] op_sel_hi:[1,0]
	v_pk_mul_f32 v[44:45], v[44:45], v[186:187] op_sel_hi:[1,0]
	v_pk_mul_f32 v[42:43], v[42:43], v[186:187] op_sel_hi:[1,0]
	v_pk_mul_f32 v[40:41], v[40:41], v[186:187] op_sel_hi:[1,0]
	v_pk_mul_f32 v[38:39], v[38:39], v[186:187] op_sel_hi:[1,0]
	v_pk_mul_f32 v[36:37], v[36:37], v[186:187] op_sel_hi:[1,0]
	v_pk_mul_f32 v[34:35], v[34:35], v[186:187] op_sel_hi:[1,0]
	v_pk_mul_f32 v[32:33], v[32:33], v[186:187] op_sel_hi:[1,0]
	v_pk_mul_f32 v[30:31], v[30:31], v[186:187] op_sel_hi:[1,0]
	v_pk_mul_f32 v[28:29], v[28:29], v[186:187] op_sel_hi:[1,0]
	v_pk_mul_f32 v[26:27], v[26:27], v[186:187] op_sel_hi:[1,0]
	v_pk_mul_f32 v[24:25], v[24:25], v[186:187] op_sel_hi:[1,0]
	v_pk_mul_f32 v[22:23], v[22:23], v[186:187] op_sel_hi:[1,0]
	v_pk_mul_f32 v[20:21], v[20:21], v[186:187] op_sel_hi:[1,0]
	v_pk_mul_f32 v[18:19], v[18:19], v[186:187] op_sel_hi:[1,0]
	v_pk_mul_f32 v[16:17], v[16:17], v[186:187] op_sel_hi:[1,0]
	v_pk_mul_f32 v[14:15], v[14:15], v[186:187] op_sel_hi:[1,0]
	v_pk_mul_f32 v[12:13], v[12:13], v[186:187] op_sel_hi:[1,0]
	v_pk_mul_f32 v[10:11], v[10:11], v[186:187] op_sel_hi:[1,0]
	v_pk_mul_f32 v[8:9], v[8:9], v[186:187] op_sel_hi:[1,0]
	v_pk_mul_f32 v[6:7], v[6:7], v[186:187] op_sel_hi:[1,0]
	v_pk_mul_f32 v[4:5], v[4:5], v[186:187] op_sel_hi:[1,0]
	v_pk_mul_f32 v[2:3], v[2:3], v[186:187] op_sel_hi:[1,0]
	v_mul_f32_e32 v225, v225, v186
.Latt2_nr_6:
	v_sub_f32_e32 v82, v82, v223
	v_sub_f32_e32 v83, v83, v223
	v_sub_f32_e32 v84, v84, v223
	v_sub_f32_e32 v85, v85, v223
	v_exp_f32_e32 v82, v82
	v_exp_f32_e32 v83, v83
	v_exp_f32_e32 v84, v84
	v_exp_f32_e32 v85, v85
	v_sub_f32_e32 v86, v86, v223
	v_sub_f32_e32 v87, v87, v223
	v_sub_f32_e32 v88, v88, v223
	v_sub_f32_e32 v89, v89, v223
	v_exp_f32_e32 v86, v86
	v_exp_f32_e32 v87, v87
	v_exp_f32_e32 v88, v88
	v_exp_f32_e32 v89, v89
	v_cvt_pk_bf16_f32 v226, v82, v83
	v_cvt_pk_bf16_f32 v227, v84, v85
	v_cvt_pk_bf16_f32 v228, v86, v87
	v_cvt_pk_bf16_f32 v229, v88, v89
	s_nop 1
	v_mfma_f32_32x32x16_bf16 v[50:65], v[236:239], v[226:229], v[50:65]
	ds_read_b128 v[236:239], v217 offset:4640
	v_sub_f32_e32 v90, v90, v223
	v_sub_f32_e32 v91, v91, v223
	v_sub_f32_e32 v92, v92, v223
	v_sub_f32_e32 v93, v93, v223
	v_exp_f32_e32 v90, v90
	v_exp_f32_e32 v91, v91
	v_mfma_f32_32x32x16_bf16 v[34:49], v[240:243], v[226:229], v[34:49]
	ds_read_b128 v[240:243], v217 offset:9248
	v_exp_f32_e32 v92, v92
	v_exp_f32_e32 v93, v93
	v_sub_f32_e32 v94, v94, v223
	v_sub_f32_e32 v95, v95, v223
	v_sub_f32_e32 v96, v96, v223
	v_sub_f32_e32 v97, v97, v223
	v_mfma_f32_32x32x16_bf16 v[18:33], v[244:247], v[226:229], v[18:33]
	ds_read_b128 v[244:247], v217 offset:13856
	v_exp_f32_e32 v94, v94
	v_exp_f32_e32 v95, v95
	v_exp_f32_e32 v96, v96
	v_exp_f32_e32 v97, v97
	v_add_f32_e32 v186, 0, v82
	v_add_f32_e32 v186, v83, v186
	v_mfma_f32_32x32x16_bf16 v[2:17], v[248:251], v[226:229], v[2:17]
	ds_read_b128 v[248:251], v217 offset:64
	v_add_f32_e32 v186, v84, v186
	v_add_f32_e32 v186, v85, v186
	v_add_f32_e32 v186, v86, v186
	v_add_f32_e32 v186, v87, v186
	v_add_f32_e32 v186, v88, v186
	v_add_f32_e32 v186, v89, v186
	v_cvt_pk_bf16_f32 v226, v90, v91
	v_cvt_pk_bf16_f32 v227, v92, v93
	v_cvt_pk_bf16_f32 v228, v94, v95
	v_cvt_pk_bf16_f32 v229, v96, v97
	s_nop 1
	v_mfma_f32_32x32x16_bf16 v[50:65], v[210:213], v[226:229], v[50:65]
	ds_read_b128 v[210:213], v217 offset:4672
	v_sub_f32_e32 v66, v66, v223
	v_sub_f32_e32 v67, v67, v223
	v_sub_f32_e32 v68, v68, v223
	v_sub_f32_e32 v69, v69, v223
	v_exp_f32_e32 v66, v66
	v_exp_f32_e32 v67, v67
	s_waitcnt lgkmcnt(4)
	v_mfma_f32_32x32x16_bf16 v[34:49], v[236:239], v[226:229], v[34:49]
	ds_read_b128 v[236:239], v217 offset:9280
	v_exp_f32_e32 v68, v68
	v_exp_f32_e32 v69, v69
	v_sub_f32_e32 v70, v70, v223
	v_sub_f32_e32 v71, v71, v223
	v_sub_f32_e32 v72, v72, v223
	v_sub_f32_e32 v73, v73, v223
	s_waitcnt lgkmcnt(4)
	v_mfma_f32_32x32x16_bf16 v[18:33], v[240:243], v[226:229], v[18:33]
	ds_read_b128 v[240:243], v217 offset:13888
	v_exp_f32_e32 v70, v70
	v_exp_f32_e32 v71, v71
	v_exp_f32_e32 v72, v72
	v_exp_f32_e32 v73, v73
	v_add_f32_e32 v186, v90, v186
	v_add_f32_e32 v186, v91, v186
	s_waitcnt lgkmcnt(4)
	v_mfma_f32_32x32x16_bf16 v[2:17], v[244:247], v[226:229], v[2:17]
	ds_read_b128 v[244:247], v217 offset:96
	v_add_f32_e32 v186, v92, v186
	v_add_f32_e32 v186, v93, v186
	v_add_f32_e32 v186, v94, v186
	v_add_f32_e32 v186, v95, v186
	v_add_f32_e32 v186, v96, v186
	v_add_f32_e32 v186, v97, v186
	v_cvt_pk_bf16_f32 v226, v66, v67
	v_cvt_pk_bf16_f32 v227, v68, v69
	v_cvt_pk_bf16_f32 v228, v70, v71
	v_cvt_pk_bf16_f32 v229, v72, v73
	s_nop 1
	s_waitcnt lgkmcnt(4)
	v_mfma_f32_32x32x16_bf16 v[50:65], v[248:251], v[226:229], v[50:65]
	ds_read_b128 v[248:251], v217 offset:4704
	v_sub_f32_e32 v74, v74, v223
	v_sub_f32_e32 v75, v75, v223
	v_sub_f32_e32 v76, v76, v223
	v_sub_f32_e32 v77, v77, v223
	v_exp_f32_e32 v74, v74
	v_exp_f32_e32 v75, v75
	s_waitcnt lgkmcnt(4)
	v_mfma_f32_32x32x16_bf16 v[34:49], v[210:213], v[226:229], v[34:49]
	ds_read_b128 v[210:213], v217 offset:9312
	v_exp_f32_e32 v76, v76
	v_exp_f32_e32 v77, v77
	v_sub_f32_e32 v78, v78, v223
	v_sub_f32_e32 v79, v79, v223
	v_sub_f32_e32 v80, v80, v223
	v_sub_f32_e32 v81, v81, v223
	s_waitcnt lgkmcnt(4)
	v_mfma_f32_32x32x16_bf16 v[18:33], v[236:239], v[226:229], v[18:33]
	ds_read_b128 v[236:239], v217 offset:13920
	v_exp_f32_e32 v78, v78
	v_exp_f32_e32 v79, v79
	v_exp_f32_e32 v80, v80
	v_exp_f32_e32 v81, v81
	v_add_f32_e32 v186, v66, v186
	v_add_f32_e32 v186, v67, v186
	s_waitcnt lgkmcnt(4)
	v_mfma_f32_32x32x16_bf16 v[2:17], v[240:243], v[226:229], v[2:17]
	v_add_f32_e32 v186, v68, v186
	v_add_f32_e32 v186, v69, v186
	v_add_f32_e32 v186, v70, v186
	v_add_f32_e32 v186, v71, v186
	v_add_f32_e32 v186, v72, v186
	v_add_f32_e32 v186, v73, v186
	v_cvt_pk_bf16_f32 v226, v74, v75
	v_cvt_pk_bf16_f32 v227, v76, v77
	v_cvt_pk_bf16_f32 v228, v78, v79
	v_cvt_pk_bf16_f32 v229, v80, v81
	s_nop 1
	s_waitcnt lgkmcnt(3)
	v_mfma_f32_32x32x16_bf16 v[50:65], v[244:247], v[226:229], v[50:65]
	v_add_f32_e32 v186, v74, v186
	v_add_f32_e32 v186, v75, v186
	s_waitcnt lgkmcnt(2)
	v_mfma_f32_32x32x16_bf16 v[34:49], v[248:251], v[226:229], v[34:49]
	v_add_f32_e32 v186, v76, v186
	v_add_f32_e32 v186, v77, v186
	s_waitcnt lgkmcnt(1)
	v_mfma_f32_32x32x16_bf16 v[18:33], v[210:213], v[226:229], v[18:33]
	v_add_f32_e32 v186, v78, v186
	v_add_f32_e32 v186, v79, v186
	s_waitcnt lgkmcnt(0)
	s_barrier
	v_mfma_f32_32x32x16_bf16 v[2:17], v[236:239], v[226:229], v[2:17]
	v_add_f32_e32 v186, v80, v186
	v_add_f32_e32 v186, v81, v186
	v_add_f32_e32 v224, v225, v186
	s_setprio 0
	s_add_i32 s13, s11, -4
	s_cmp_ge_u32 s13, s5
	s_cbranch_scc0 .Latt2_A_loop
	s_branch .LBB0_40

.Latt2_nr_9:
	v_sub_f32_e32 v82, v82, v223
	v_sub_f32_e32 v83, v83, v223
	v_sub_f32_e32 v84, v84, v223
	v_sub_f32_e32 v85, v85, v223
	v_exp_f32_e32 v82, v82
	v_exp_f32_e32 v83, v83
	v_exp_f32_e32 v84, v84
	v_exp_f32_e32 v85, v85
	v_sub_f32_e32 v86, v86, v223
	v_sub_f32_e32 v87, v87, v223
	v_sub_f32_e32 v88, v88, v223
	v_sub_f32_e32 v89, v89, v223
	v_exp_f32_e32 v86, v86
	v_exp_f32_e32 v87, v87
	v_exp_f32_e32 v88, v88
	v_exp_f32_e32 v89, v89
	v_cvt_pk_bf16_f32 v226, v82, v83
	v_cvt_pk_bf16_f32 v227, v84, v85
	v_cvt_pk_bf16_f32 v228, v86, v87
	v_cvt_pk_bf16_f32 v229, v88, v89
	s_nop 1
	v_mfma_f32_32x32x16_bf16 v[50:65], v[236:239], v[226:229], v[50:65]
	ds_read_b128 v[236:239], v216 offset:30240
	v_sub_f32_e32 v90, v90, v223
	v_sub_f32_e32 v91, v91, v223
	v_sub_f32_e32 v92, v92, v223
	v_sub_f32_e32 v93, v93, v223
	v_exp_f32_e32 v90, v90
	v_exp_f32_e32 v91, v91
	v_mfma_f32_32x32x16_bf16 v[34:49], v[240:243], v[226:229], v[34:49]
	ds_read_b128 v[240:243], v216 offset:34848
	v_exp_f32_e32 v92, v92
	v_exp_f32_e32 v93, v93
	v_sub_f32_e32 v94, v94, v223
	v_sub_f32_e32 v95, v95, v223
	v_sub_f32_e32 v96, v96, v223
	v_sub_f32_e32 v97, v97, v223
	v_mfma_f32_32x32x16_bf16 v[18:33], v[244:247], v[226:229], v[18:33]
	ds_read_b128 v[244:247], v216 offset:39456
	v_exp_f32_e32 v94, v94
	v_exp_f32_e32 v95, v95
	v_exp_f32_e32 v96, v96
	v_exp_f32_e32 v97, v97
	v_add_f32_e32 v186, 0, v82
	v_add_f32_e32 v186, v83, v186
	v_mfma_f32_32x32x16_bf16 v[2:17], v[248:251], v[226:229], v[2:17]
	ds_read_b128 v[248:251], v216 offset:25664
	v_add_f32_e32 v186, v84, v186
	v_add_f32_e32 v186, v85, v186
	v_add_f32_e32 v186, v86, v186
	v_add_f32_e32 v186, v87, v186
	v_add_f32_e32 v186, v88, v186
	v_add_f32_e32 v186, v89, v186
	v_cvt_pk_bf16_f32 v226, v90, v91
	v_cvt_pk_bf16_f32 v227, v92, v93
	v_cvt_pk_bf16_f32 v228, v94, v95
	v_cvt_pk_bf16_f32 v229, v96, v97
	s_nop 1
	v_mfma_f32_32x32x16_bf16 v[50:65], v[210:213], v[226:229], v[50:65]
	ds_read_b128 v[210:213], v216 offset:30272
	v_sub_f32_e32 v66, v66, v223
	v_sub_f32_e32 v67, v67, v223
	v_sub_f32_e32 v68, v68, v223
	v_sub_f32_e32 v69, v69, v223
	v_exp_f32_e32 v66, v66
	v_exp_f32_e32 v67, v67
	s_waitcnt lgkmcnt(4)
	v_mfma_f32_32x32x16_bf16 v[34:49], v[236:239], v[226:229], v[34:49]
	ds_read_b128 v[236:239], v216 offset:34880
	v_exp_f32_e32 v68, v68
	v_exp_f32_e32 v69, v69
	v_sub_f32_e32 v70, v70, v223
	v_sub_f32_e32 v71, v71, v223
	v_sub_f32_e32 v72, v72, v223
	v_sub_f32_e32 v73, v73, v223
	s_waitcnt lgkmcnt(4)
	v_mfma_f32_32x32x16_bf16 v[18:33], v[240:243], v[226:229], v[18:33]
	ds_read_b128 v[240:243], v216 offset:39488
	v_exp_f32_e32 v70, v70
	v_exp_f32_e32 v71, v71
	v_exp_f32_e32 v72, v72
	v_exp_f32_e32 v73, v73
	v_add_f32_e32 v186, v90, v186
	v_add_f32_e32 v186, v91, v186
	s_waitcnt lgkmcnt(4)
	v_mfma_f32_32x32x16_bf16 v[2:17], v[244:247], v[226:229], v[2:17]
	ds_read_b128 v[244:247], v216 offset:25696
	v_add_f32_e32 v186, v92, v186
	v_add_f32_e32 v186, v93, v186
	v_add_f32_e32 v186, v94, v186
	v_add_f32_e32 v186, v95, v186
	v_add_f32_e32 v186, v96, v186
	v_add_f32_e32 v186, v97, v186
	v_cvt_pk_bf16_f32 v226, v66, v67
	v_cvt_pk_bf16_f32 v227, v68, v69
	v_cvt_pk_bf16_f32 v228, v70, v71
	v_cvt_pk_bf16_f32 v229, v72, v73
	s_nop 1
	s_waitcnt lgkmcnt(4)
	v_mfma_f32_32x32x16_bf16 v[50:65], v[248:251], v[226:229], v[50:65]
	ds_read_b128 v[248:251], v216 offset:30304
	v_sub_f32_e32 v74, v74, v223
	v_sub_f32_e32 v75, v75, v223
	v_sub_f32_e32 v76, v76, v223
	v_sub_f32_e32 v77, v77, v223
	v_exp_f32_e32 v74, v74
	v_exp_f32_e32 v75, v75
	s_waitcnt lgkmcnt(4)
	v_mfma_f32_32x32x16_bf16 v[34:49], v[210:213], v[226:229], v[34:49]
	ds_read_b128 v[210:213], v216 offset:34912
	v_exp_f32_e32 v76, v76
	v_exp_f32_e32 v77, v77
	v_sub_f32_e32 v78, v78, v223
	v_sub_f32_e32 v79, v79, v223
	v_sub_f32_e32 v80, v80, v223
	v_sub_f32_e32 v81, v81, v223
	s_waitcnt lgkmcnt(4)
	v_mfma_f32_32x32x16_bf16 v[18:33], v[236:239], v[226:229], v[18:33]
	ds_read_b128 v[236:239], v216 offset:39520
	v_exp_f32_e32 v78, v78
	v_exp_f32_e32 v79, v79
	v_exp_f32_e32 v80, v80
	v_exp_f32_e32 v81, v81
	v_add_f32_e32 v186, v66, v186
	v_add_f32_e32 v186, v67, v186
	s_waitcnt lgkmcnt(4)
	v_mfma_f32_32x32x16_bf16 v[2:17], v[240:243], v[226:229], v[2:17]
	v_add_f32_e32 v186, v68, v186
	v_add_f32_e32 v186, v69, v186
	v_add_f32_e32 v186, v70, v186
	v_add_f32_e32 v186, v71, v186
	v_add_f32_e32 v186, v72, v186
	v_add_f32_e32 v186, v73, v186
	v_cvt_pk_bf16_f32 v226, v74, v75
	v_cvt_pk_bf16_f32 v227, v76, v77
	v_cvt_pk_bf16_f32 v228, v78, v79
	v_cvt_pk_bf16_f32 v229, v80, v81
	s_nop 1
	s_waitcnt lgkmcnt(3)
	v_mfma_f32_32x32x16_bf16 v[50:65], v[244:247], v[226:229], v[50:65]
	v_add_f32_e32 v186, v74, v186
	v_add_f32_e32 v186, v75, v186
	s_waitcnt lgkmcnt(2)
	v_mfma_f32_32x32x16_bf16 v[34:49], v[248:251], v[226:229], v[34:49]
	v_add_f32_e32 v186, v76, v186
	v_add_f32_e32 v186, v77, v186
	s_waitcnt lgkmcnt(1)
	v_mfma_f32_32x32x16_bf16 v[18:33], v[210:213], v[226:229], v[18:33]
	v_add_f32_e32 v186, v78, v186
	v_add_f32_e32 v186, v79, v186
	s_waitcnt lgkmcnt(0)
	s_barrier
	v_mfma_f32_32x32x16_bf16 v[2:17], v[236:239], v[226:229], v[2:17]
	v_add_f32_e32 v186, v80, v186
	v_add_f32_e32 v186, v81, v186
	v_add_f32_e32 v225, v224, v186
	s_setprio 0
	s_add_i32 s13, s11, -2
	s_cmp_ge_u32 s13, s5
	s_cbranch_scc1 .Latt2_ws_10
	s_waitcnt vmcnt(9)
	ds_write_b128 v219, v[118:121]
	s_waitcnt vmcnt(8)
	ds_write_b128 v220, v[122:125]
	s_waitcnt vmcnt(7)
	ds_write_b128 v221, v[130:133]
	s_waitcnt vmcnt(6)
	ds_write_b128 v222, v[134:137] offset:25600
	s_waitcnt vmcnt(5)
	ds_write_b128 v222, v[138:141] offset:34816

.Latt2_wl_11:
	s_mov_b64 s[14:15], 0xc000
	v_lshl_add_u64 v[206:207], v[206:207], 0, s[14:15]
	s_mov_b64 s[14:15], 0x100
	s_add_i32 s11, s11, 2
	v_lshl_add_u64 v[204:205], v[204:205], 0, s[14:15]
	v_lshl_add_u64 v[208:209], v[208:209], 0, s[14:15]
	ds_read_b128 v[226:229], v215 offset:44032
	ds_read_b128 v[236:239], v215 offset:56832
	ds_read_b128 v[240:243], v215 offset:44064
	ds_read_b128 v[244:247], v215 offset:56864
	ds_read_b128 v[248:251], v215 offset:44096
	ds_read_b128 v[210:213], v215 offset:56896
	s_waitcnt lgkmcnt(5)
	v_mfma_f32_32x32x16_bf16 v[82:97], v[226:229], v[126:129], 0
	ds_read_b128 v[226:229], v215 offset:44128
	s_waitcnt lgkmcnt(5)
	v_mfma_f32_32x32x16_bf16 v[66:81], v[236:239], v[126:129], 0
	ds_read_b128 v[236:239], v215 offset:56928
	s_waitcnt lgkmcnt(5)
	v_mfma_f32_32x32x16_bf16 v[82:97], v[240:243], v[142:145], v[82:97]
	ds_read_b128 v[240:243], v215 offset:44160
	s_waitcnt lgkmcnt(5)
	v_mfma_f32_32x32x16_bf16 v[66:81], v[244:247], v[142:145], v[66:81]
	ds_read_b128 v[244:247], v215 offset:56960
	s_waitcnt lgkmcnt(5)
	v_mfma_f32_32x32x16_bf16 v[82:97], v[248:251], v[146:149], v[82:97]
	ds_read_b128 v[248:251], v215 offset:44192
	s_waitcnt lgkmcnt(5)
	v_mfma_f32_32x32x16_bf16 v[66:81], v[210:213], v[146:149], v[66:81]
	ds_read_b128 v[210:213], v215 offset:56992
	s_waitcnt lgkmcnt(5)
	v_mfma_f32_32x32x16_bf16 v[82:97], v[226:229], v[150:153], v[82:97]
	ds_read_b128 v[226:229], v215 offset:44224
	s_waitcnt lgkmcnt(5)
	v_mfma_f32_32x32x16_bf16 v[66:81], v[236:239], v[150:153], v[66:81]
	ds_read_b128 v[236:239], v215 offset:57024
	s_waitcnt lgkmcnt(5)
	v_mfma_f32_32x32x16_bf16 v[82:97], v[240:243], v[154:157], v[82:97]
	ds_read_b128 v[240:243], v215 offset:44256
	s_waitcnt lgkmcnt(5)
	v_mfma_f32_32x32x16_bf16 v[66:81], v[244:247], v[154:157], v[66:81]
	ds_read_b128 v[244:247], v215 offset:57056
	s_waitcnt lgkmcnt(5)
	v_mfma_f32_32x32x16_bf16 v[82:97], v[248:251], v[158:161], v[82:97]
	ds_read_b128 v[248:251], v215 offset:44288
	s_waitcnt lgkmcnt(5)
	v_mfma_f32_32x32x16_bf16 v[66:81], v[210:213], v[158:161], v[66:81]
	ds_read_b128 v[210:213], v215 offset:57088
	s_waitcnt lgkmcnt(5)
	v_mfma_f32_32x32x16_bf16 v[82:97], v[226:229], v[162:165], v[82:97]
	ds_read_b128 v[226:229], v215 offset:44320
	s_waitcnt lgkmcnt(5)
	v_mfma_f32_32x32x16_bf16 v[66:81], v[236:239], v[162:165], v[66:81]
	ds_read_b128 v[236:239], v215 offset:57120
	s_waitcnt lgkmcnt(5)
	v_mfma_f32_32x32x16_bf16 v[82:97], v[240:243], v[166:169], v[82:97]
	ds_read_b128 v[240:243], v215 offset:44352
	s_waitcnt lgkmcnt(5)
	v_mfma_f32_32x32x16_bf16 v[66:81], v[244:247], v[166:169], v[66:81]
	ds_read_b128 v[244:247], v215 offset:57152
	s_waitcnt lgkmcnt(5)
	v_mfma_f32_32x32x16_bf16 v[82:97], v[248:251], v[170:173], v[82:97]
	ds_read_b128 v[248:251], v215 offset:44384
	s_waitcnt lgkmcnt(5)
	v_mfma_f32_32x32x16_bf16 v[66:81], v[210:213], v[170:173], v[66:81]
	ds_read_b128 v[210:213], v215 offset:57184
	s_waitcnt lgkmcnt(5)
	v_mfma_f32_32x32x16_bf16 v[82:97], v[226:229], v[174:177], v[82:97]
	s_waitcnt lgkmcnt(4)
	v_mfma_f32_32x32x16_bf16 v[66:81], v[236:239], v[174:177], v[66:81]
	s_waitcnt lgkmcnt(3)
	v_mfma_f32_32x32x16_bf16 v[82:97], v[240:243], v[178:181], v[82:97]
	s_waitcnt lgkmcnt(2)
	v_mfma_f32_32x32x16_bf16 v[66:81], v[244:247], v[178:181], v[66:81]
	s_waitcnt lgkmcnt(1)
	v_mfma_f32_32x32x16_bf16 v[82:97], v[248:251], v[182:185], v[82:97]
	s_waitcnt lgkmcnt(0)
	s_barrier
	v_mfma_f32_32x32x16_bf16 v[66:81], v[210:213], v[182:185], v[66:81]
	s_setprio 2
	ds_read_b128 v[236:239], v217
	ds_read_b128 v[240:243], v217 offset:4608
	ds_read_b128 v[244:247], v217 offset:9216
	ds_read_b128 v[248:251], v217 offset:13824
	ds_read_b128 v[210:213], v217 offset:32
	s_nop 4
	v_max_f32_e32 v186, v83, v83
	v_max_f32_e32 v187, v82, v82
	v_max_f32_e32 v186, v187, v186
	v_max3_f32 v186, v186, v84, v85
	v_max3_f32 v186, v186, v86, v87
	v_max3_f32 v186, v186, v88, v89
	v_max3_f32 v186, v186, v90, v91
	v_max3_f32 v186, v186, v92, v93
	v_max3_f32 v186, v186, v94, v95
	v_max3_f32 v186, v186, v96, v97
	v_max3_f32 v186, v186, v66, v67
	v_max3_f32 v186, v186, v68, v69
	v_max3_f32 v186, v186, v70, v71
	v_max3_f32 v186, v186, v72, v73
	v_max3_f32 v186, v186, v74, v75
	v_max3_f32 v186, v186, v76, v77
	v_max3_f32 v186, v186, v78, v79
	v_max3_f32 v186, v186, v80, v81
	ds_bpermute_b32 v187, v214, v186
	s_waitcnt lgkmcnt(0)
	v_max_f32_e32 v187, v187, v187
	v_max_f32_e32 v187, v186, v187
	v_add_f32_e32 v186, 0x41380000, v223
	v_cmp_gt_f32_e32 vcc, v187, v186
	s_cbranch_vccz .Latt2_nr_12
	v_max_f32_e32 v186, v187, v187
	v_max_f32_e32 v187, v223, v223
	v_max_f32_e32 v187, v187, v186
	v_sub_f32_e32 v186, v223, v187
	v_exp_f32_e32 v186, v186
	v_mov_b32_e32 v223, v187
	v_pk_mul_f32 v[64:65], v[64:65], v[186:187] op_sel_hi:[1,0]
	v_pk_mul_f32 v[62:63], v[62:63], v[186:187] op_sel_hi:[1,0]
	v_pk_mul_f32 v[60:61], v[60:61], v[186:187] op_sel_hi:[1,0]
	v_pk_mul_f32 v[58:59], v[58:59], v[186:187] op_sel_hi:[1,0]
	v_pk_mul_f32 v[56:57], v[56:57], v[186:187] op_sel_hi:[1,0]
	v_pk_mul_f32 v[54:55], v[54:55], v[186:187] op_sel_hi:[1,0]
	v_pk_mul_f32 v[52:53], v[52:53], v[186:187] op_sel_hi:[1,0]
	v_pk_mul_f32 v[50:51], v[50:51], v[186:187] op_sel_hi:[1,0]
	v_pk_mul_f32 v[48:49], v[48:49], v[186:187] op_sel_hi:[1,0]
	v_pk_mul_f32 v[46:47], v[46:47], v[186:187] op_sel_hi:[1,0]
	v_pk_mul_f32 v[44:45], v[44:45], v[186:187] op_sel_hi:[1,0]
	v_pk_mul_f32 v[42:43], v[42:43], v[186:187] op_sel_hi:[1,0]
	v_pk_mul_f32 v[40:41], v[40:41], v[186:187] op_sel_hi:[1,0]
	v_pk_mul_f32 v[38:39], v[38:39], v[186:187] op_sel_hi:[1,0]
	v_pk_mul_f32 v[36:37], v[36:37], v[186:187] op_sel_hi:[1,0]
	v_pk_mul_f32 v[34:35], v[34:35], v[186:187] op_sel_hi:[1,0]
	v_pk_mul_f32 v[32:33], v[32:33], v[186:187] op_sel_hi:[1,0]
	v_pk_mul_f32 v[30:31], v[30:31], v[186:187] op_sel_hi:[1,0]
	v_pk_mul_f32 v[28:29], v[28:29], v[186:187] op_sel_hi:[1,0]
	v_pk_mul_f32 v[26:27], v[26:27], v[186:187] op_sel_hi:[1,0]
	v_pk_mul_f32 v[24:25], v[24:25], v[186:187] op_sel_hi:[1,0]
	v_pk_mul_f32 v[22:23], v[22:23], v[186:187] op_sel_hi:[1,0]
	v_pk_mul_f32 v[20:21], v[20:21], v[186:187] op_sel_hi:[1,0]
	v_pk_mul_f32 v[18:19], v[18:19], v[186:187] op_sel_hi:[1,0]
	v_pk_mul_f32 v[16:17], v[16:17], v[186:187] op_sel_hi:[1,0]
	v_pk_mul_f32 v[14:15], v[14:15], v[186:187] op_sel_hi:[1,0]
	v_pk_mul_f32 v[12:13], v[12:13], v[186:187] op_sel_hi:[1,0]
	v_pk_mul_f32 v[10:11], v[10:11], v[186:187] op_sel_hi:[1,0]
	v_pk_mul_f32 v[8:9], v[8:9], v[186:187] op_sel_hi:[1,0]
	v_pk_mul_f32 v[6:7], v[6:7], v[186:187] op_sel_hi:[1,0]
	v_pk_mul_f32 v[4:5], v[4:5], v[186:187] op_sel_hi:[1,0]
	v_pk_mul_f32 v[2:3], v[2:3], v[186:187] op_sel_hi:[1,0]
	v_mul_f32_e32 v225, v225, v186
.Latt2_nr_12:
	v_sub_f32_e32 v82, v82, v223
	v_sub_f32_e32 v83, v83, v223
	v_sub_f32_e32 v84, v84, v223
	v_sub_f32_e32 v85, v85, v223
	v_exp_f32_e32 v82, v82
	v_exp_f32_e32 v83, v83
	v_exp_f32_e32 v84, v84
	v_exp_f32_e32 v85, v85
	v_sub_f32_e32 v86, v86, v223
	v_sub_f32_e32 v87, v87, v223
	v_sub_f32_e32 v88, v88, v223
	v_sub_f32_e32 v89, v89, v223
	v_exp_f32_e32 v86, v86
	v_exp_f32_e32 v87, v87
	v_exp_f32_e32 v88, v88
	v_exp_f32_e32 v89, v89
	v_cvt_pk_bf16_f32 v226, v82, v83
	v_cvt_pk_bf16_f32 v227, v84, v85
	v_cvt_pk_bf16_f32 v228, v86, v87
	v_cvt_pk_bf16_f32 v229, v88, v89
	s_nop 1
	v_mfma_f32_32x32x16_bf16 v[50:65], v[236:239], v[226:229], v[50:65]
	ds_read_b128 v[236:239], v217 offset:4640
	v_sub_f32_e32 v90, v90, v223
	v_sub_f32_e32 v91, v91, v223
	v_sub_f32_e32 v92, v92, v223
	v_sub_f32_e32 v93, v93, v223
	v_exp_f32_e32 v90, v90
	v_exp_f32_e32 v91, v91
	v_mfma_f32_32x32x16_bf16 v[34:49], v[240:243], v[226:229], v[34:49]
	ds_read_b128 v[240:243], v217 offset:9248
	v_exp_f32_e32 v92, v92
	v_exp_f32_e32 v93, v93
	v_sub_f32_e32 v94, v94, v223
	v_sub_f32_e32 v95, v95, v223
	v_sub_f32_e32 v96, v96, v223
	v_sub_f32_e32 v97, v97, v223
	v_mfma_f32_32x32x16_bf16 v[18:33], v[244:247], v[226:229], v[18:33]
	ds_read_b128 v[244:247], v217 offset:13856
	v_exp_f32_e32 v94, v94
	v_exp_f32_e32 v95, v95
	v_exp_f32_e32 v96, v96
	v_exp_f32_e32 v97, v97
	v_add_f32_e32 v186, 0, v82
	v_add_f32_e32 v186, v83, v186
	v_mfma_f32_32x32x16_bf16 v[2:17], v[248:251], v[226:229], v[2:17]
	ds_read_b128 v[248:251], v217 offset:64
	v_add_f32_e32 v186, v84, v186
	v_add_f32_e32 v186, v85, v186
	v_add_f32_e32 v186, v86, v186
	v_add_f32_e32 v186, v87, v186
	v_add_f32_e32 v186, v88, v186
	v_add_f32_e32 v186, v89, v186
	v_cvt_pk_bf16_f32 v226, v90, v91
	v_cvt_pk_bf16_f32 v227, v92, v93
	v_cvt_pk_bf16_f32 v228, v94, v95
	v_cvt_pk_bf16_f32 v229, v96, v97
	s_nop 1
	v_mfma_f32_32x32x16_bf16 v[50:65], v[210:213], v[226:229], v[50:65]
	ds_read_b128 v[210:213], v217 offset:4672
	v_sub_f32_e32 v66, v66, v223
	v_sub_f32_e32 v67, v67, v223
	v_sub_f32_e32 v68, v68, v223
	v_sub_f32_e32 v69, v69, v223
	v_exp_f32_e32 v66, v66
	v_exp_f32_e32 v67, v67
	s_waitcnt lgkmcnt(4)
	v_mfma_f32_32x32x16_bf16 v[34:49], v[236:239], v[226:229], v[34:49]
	ds_read_b128 v[236:239], v217 offset:9280
	v_exp_f32_e32 v68, v68
	v_exp_f32_e32 v69, v69
	v_sub_f32_e32 v70, v70, v223
	v_sub_f32_e32 v71, v71, v223
	v_sub_f32_e32 v72, v72, v223
	v_sub_f32_e32 v73, v73, v223
	s_waitcnt lgkmcnt(4)
	v_mfma_f32_32x32x16_bf16 v[18:33], v[240:243], v[226:229], v[18:33]
	ds_read_b128 v[240:243], v217 offset:13888
	v_exp_f32_e32 v70, v70
	v_exp_f32_e32 v71, v71
	v_exp_f32_e32 v72, v72
	v_exp_f32_e32 v73, v73
	v_add_f32_e32 v186, v90, v186
	v_add_f32_e32 v186, v91, v186
	s_waitcnt lgkmcnt(4)
	v_mfma_f32_32x32x16_bf16 v[2:17], v[244:247], v[226:229], v[2:17]
	ds_read_b128 v[244:247], v217 offset:96
	v_add_f32_e32 v186, v92, v186
	v_add_f32_e32 v186, v93, v186
	v_add_f32_e32 v186, v94, v186
	v_add_f32_e32 v186, v95, v186
	v_add_f32_e32 v186, v96, v186
	v_add_f32_e32 v186, v97, v186
	v_cvt_pk_bf16_f32 v226, v66, v67
	v_cvt_pk_bf16_f32 v227, v68, v69
	v_cvt_pk_bf16_f32 v228, v70, v71
	v_cvt_pk_bf16_f32 v229, v72, v73
	s_nop 1
	s_waitcnt lgkmcnt(4)
	v_mfma_f32_32x32x16_bf16 v[50:65], v[248:251], v[226:229], v[50:65]
	ds_read_b128 v[248:251], v217 offset:4704
	v_sub_f32_e32 v74, v74, v223
	v_sub_f32_e32 v75, v75, v223
	v_sub_f32_e32 v76, v76, v223
	v_sub_f32_e32 v77, v77, v223
	v_exp_f32_e32 v74, v74
	v_exp_f32_e32 v75, v75
	s_waitcnt lgkmcnt(4)
	v_mfma_f32_32x32x16_bf16 v[34:49], v[210:213], v[226:229], v[34:49]
	ds_read_b128 v[210:213], v217 offset:9312
	v_exp_f32_e32 v76, v76
	v_exp_f32_e32 v77, v77
	v_sub_f32_e32 v78, v78, v223
	v_sub_f32_e32 v79, v79, v223
	v_sub_f32_e32 v80, v80, v223
	v_sub_f32_e32 v81, v81, v223
	s_waitcnt lgkmcnt(4)
	v_mfma_f32_32x32x16_bf16 v[18:33], v[236:239], v[226:229], v[18:33]
	ds_read_b128 v[236:239], v217 offset:13920
	v_exp_f32_e32 v78, v78
	v_exp_f32_e32 v79, v79
	v_exp_f32_e32 v80, v80
	v_exp_f32_e32 v81, v81
	v_add_f32_e32 v186, v66, v186
	v_add_f32_e32 v186, v67, v186
	s_waitcnt lgkmcnt(4)
	v_mfma_f32_32x32x16_bf16 v[2:17], v[240:243], v[226:229], v[2:17]
	v_add_f32_e32 v186, v68, v186
	v_add_f32_e32 v186, v69, v186
	v_add_f32_e32 v186, v70, v186
	v_add_f32_e32 v186, v71, v186
	v_add_f32_e32 v186, v72, v186
	v_add_f32_e32 v186, v73, v186
	v_cvt_pk_bf16_f32 v226, v74, v75
	v_cvt_pk_bf16_f32 v227, v76, v77
	v_cvt_pk_bf16_f32 v228, v78, v79
	v_cvt_pk_bf16_f32 v229, v80, v81
	s_nop 1
	s_waitcnt lgkmcnt(3)
	v_mfma_f32_32x32x16_bf16 v[50:65], v[244:247], v[226:229], v[50:65]
	v_add_f32_e32 v186, v74, v186
	v_add_f32_e32 v186, v75, v186
	s_waitcnt lgkmcnt(2)
	v_mfma_f32_32x32x16_bf16 v[34:49], v[248:251], v[226:229], v[34:49]
	v_add_f32_e32 v186, v76, v186
	v_add_f32_e32 v186, v77, v186
	s_waitcnt lgkmcnt(1)
	v_mfma_f32_32x32x16_bf16 v[18:33], v[210:213], v[226:229], v[18:33]
	v_add_f32_e32 v186, v78, v186
	v_add_f32_e32 v186, v79, v186
	s_waitcnt lgkmcnt(0)
	v_mfma_f32_32x32x16_bf16 v[2:17], v[236:239], v[226:229], v[2:17]
	v_add_f32_e32 v186, v80, v186
	v_add_f32_e32 v186, v81, v186
	v_add_f32_e32 v224, v225, v186
	s_setprio 0
	s_add_i32 s13, s11, -4
	s_cmp_ge_u32 s13, s5
	s_cbranch_scc1 .LBB0_40
	s_barrier
	s_add_i32 s13, s11, -1
	s_cmp_ge_u32 s13, s5
	s_cbranch_scc1 .Latt2_wt_13
	s_waitcnt vmcnt(9)
	ds_write_b128 v219, v[102:105] offset:44032
	s_waitcnt vmcnt(8)
	ds_write_b128 v220, v[106:109] offset:44032
	s_waitcnt vmcnt(7)
	ds_write_b128 v221, v[114:117] offset:44032
	s_waitcnt vmcnt(6)
	ds_write_b128 v201, v[98:101]
	s_waitcnt vmcnt(5)
	ds_write_b128 v201, v[110:113] offset:9216
	v_add_co_u32_e32 v186, vcc, 0xffff6000, v206
	s_nop 1
	v_addc_co_u32_e32 v187, vcc, -1, v207, vcc
	global_load_dwordx4 v[102:105], v[186:187], off
	v_add_co_u32_e32 v186, vcc, 0xffff8000, v206
	s_nop 1
	v_addc_co_u32_e32 v187, vcc, -1, v207, vcc
	global_load_dwordx4 v[106:109], v[186:187], off
	v_add_co_u32_e32 v186, vcc, 0xffffa000, v206
	s_nop 1
	v_addc_co_u32_e32 v187, vcc, -1, v207, vcc
	global_load_dwordx4 v[114:117], v[186:187], off
	global_load_dwordx4 v[98:101], v[204:205], off offset:384
	global_load_dwordx4 v[110:113], v[208:209], off offset:384
	s_branch .Latt2_wd_14
